# v41: v26 with non-temporal loads and stores in the hand-written weight-conversion items (P0 groups 0/1 and P4 group 3)
# speedup vs baseline: 1.0113x; 1.0113x over previous
.Lcv0_go:
	s_mul_i32 s1, s17, s12
	s_add_i32 s1, s1, s18
	s_lshl_b32 s1, s1, 2
	s_nop 3
	s_add_u32 s10, s10, s1
	s_addc_u32 s11, s11, 0
	v_mul_lo_u32 v107, v102, s12
	v_add_lshl_u32 v107, v107, v101, 2
	s_lshl_b32 s19, s12, 3
	global_load_dword v16, v107, s[10:11] nt
	s_add_u32 s10, s10, s19
	s_addc_u32 s11, s11, 0
	global_load_dword v17, v107, s[10:11] nt
	s_add_u32 s10, s10, s19
	s_addc_u32 s11, s11, 0
	global_load_dword v18, v107, s[10:11] nt
	s_add_u32 s10, s10, s19
	s_addc_u32 s11, s11, 0
	global_load_dword v19, v107, s[10:11] nt
	s_add_u32 s10, s10, s19
	s_addc_u32 s11, s11, 0
	global_load_dword v20, v107, s[10:11] nt
	s_add_u32 s10, s10, s19
	s_addc_u32 s11, s11, 0
	global_load_dword v21, v107, s[10:11] nt
	s_add_u32 s10, s10, s19
	s_addc_u32 s11, s11, 0
	global_load_dword v22, v107, s[10:11] nt
	s_add_u32 s10, s10, s19
	s_addc_u32 s11, s11, 0
	global_load_dword v23, v107, s[10:11] nt
	s_add_u32 s10, s10, s19
	s_addc_u32 s11, s11, 0
	global_load_dword v24, v107, s[10:11] nt
	s_add_u32 s10, s10, s19
	s_addc_u32 s11, s11, 0
	global_load_dword v25, v107, s[10:11] nt
	s_add_u32 s10, s10, s19
	s_addc_u32 s11, s11, 0
	global_load_dword v26, v107, s[10:11] nt
	s_add_u32 s10, s10, s19
	s_addc_u32 s11, s11, 0
	global_load_dword v27, v107, s[10:11] nt
	s_add_u32 s10, s10, s19
	s_addc_u32 s11, s11, 0
	global_load_dword v28, v107, s[10:11] nt
	s_add_u32 s10, s10, s19
	s_addc_u32 s11, s11, 0
	global_load_dword v29, v107, s[10:11] nt
	s_add_u32 s10, s10, s19
	s_addc_u32 s11, s11, 0
	global_load_dword v30, v107, s[10:11] nt
	s_add_u32 s10, s10, s19
	s_addc_u32 s11, s11, 0
	global_load_dword v31, v107, s[10:11] nt
	s_add_u32 s10, s10, s19
	s_addc_u32 s11, s11, 0
	global_load_dword v32, v107, s[10:11] nt
	s_add_u32 s10, s10, s19
	s_addc_u32 s11, s11, 0
	global_load_dword v33, v107, s[10:11] nt
	s_add_u32 s10, s10, s19
	s_addc_u32 s11, s11, 0
	global_load_dword v34, v107, s[10:11] nt
	s_add_u32 s10, s10, s19
	s_addc_u32 s11, s11, 0
	global_load_dword v35, v107, s[10:11] nt
	s_add_u32 s10, s10, s19
	s_addc_u32 s11, s11, 0
	global_load_dword v36, v107, s[10:11] nt
	s_add_u32 s10, s10, s19
	s_addc_u32 s11, s11, 0
	global_load_dword v37, v107, s[10:11] nt
	s_add_u32 s10, s10, s19
	s_addc_u32 s11, s11, 0
	global_load_dword v38, v107, s[10:11] nt
	s_add_u32 s10, s10, s19
	s_addc_u32 s11, s11, 0
	global_load_dword v39, v107, s[10:11] nt
	s_add_u32 s10, s10, s19
	s_addc_u32 s11, s11, 0
	global_load_dword v40, v107, s[10:11] nt
	s_add_u32 s10, s10, s19
	s_addc_u32 s11, s11, 0
	global_load_dword v41, v107, s[10:11] nt
	s_add_u32 s10, s10, s19
	s_addc_u32 s11, s11, 0
	global_load_dword v42, v107, s[10:11] nt
	s_add_u32 s10, s10, s19
	s_addc_u32 s11, s11, 0
	global_load_dword v43, v107, s[10:11] nt
	s_add_u32 s10, s10, s19
	s_addc_u32 s11, s11, 0
	global_load_dword v44, v107, s[10:11] nt
	s_add_u32 s10, s10, s19
	s_addc_u32 s11, s11, 0
	global_load_dword v45, v107, s[10:11] nt
	s_add_u32 s10, s10, s19
	s_addc_u32 s11, s11, 0
	global_load_dword v46, v107, s[10:11] nt
	s_add_u32 s10, s10, s19
	s_addc_u32 s11, s11, 0
	global_load_dword v47, v107, s[10:11] nt
	s_mul_i32 s1, s16, s13
	s_add_i32 s1, s1, s17
	s_lshl_b32 s1, s1, 1
	s_add_u32 s14, s14, s1
	s_addc_u32 s15, s15, 0
	v_mul_lo_u32 v108, v105, s13
	v_lshl_add_u32 v80, v104, 3, v108
	v_lshlrev_b32_e32 v108, 1, v80
	s_lshl_b32 s19, s13, 4
	s_waitcnt vmcnt(31)
	ds_write_b32 v103, v16 offset:0
	s_waitcnt vmcnt(30)
	ds_write_b32 v103, v17 offset:264
	s_waitcnt vmcnt(29)
	ds_write_b32 v103, v18 offset:528
	s_waitcnt vmcnt(28)
	ds_write_b32 v103, v19 offset:792
	s_waitcnt vmcnt(27)
	ds_write_b32 v103, v20 offset:1056
	s_waitcnt vmcnt(26)
	ds_write_b32 v103, v21 offset:1320
	s_waitcnt vmcnt(25)
	ds_write_b32 v103, v22 offset:1584
	s_waitcnt vmcnt(24)
	ds_write_b32 v103, v23 offset:1848
	s_waitcnt vmcnt(23)
	ds_write_b32 v103, v24 offset:2112
	s_waitcnt vmcnt(22)
	ds_write_b32 v103, v25 offset:2376
	s_waitcnt vmcnt(21)
	ds_write_b32 v103, v26 offset:2640
	s_waitcnt vmcnt(20)
	ds_write_b32 v103, v27 offset:2904
	s_waitcnt vmcnt(19)
	ds_write_b32 v103, v28 offset:3168
	s_waitcnt vmcnt(18)
	ds_write_b32 v103, v29 offset:3432
	s_waitcnt vmcnt(17)
	ds_write_b32 v103, v30 offset:3696
	s_waitcnt vmcnt(16)
	ds_write_b32 v103, v31 offset:3960
	s_waitcnt vmcnt(15)
	ds_write_b32 v103, v32 offset:4224
	s_waitcnt vmcnt(14)
	ds_write_b32 v103, v33 offset:4488
	s_waitcnt vmcnt(13)
	ds_write_b32 v103, v34 offset:4752
	s_waitcnt vmcnt(12)
	ds_write_b32 v103, v35 offset:5016
	s_waitcnt vmcnt(11)
	ds_write_b32 v103, v36 offset:5280
	s_waitcnt vmcnt(10)
	ds_write_b32 v103, v37 offset:5544
	s_waitcnt vmcnt(9)
	ds_write_b32 v103, v38 offset:5808
	s_waitcnt vmcnt(8)
	ds_write_b32 v103, v39 offset:6072
	s_waitcnt vmcnt(7)
	ds_write_b32 v103, v40 offset:6336
	s_waitcnt vmcnt(6)
	ds_write_b32 v103, v41 offset:6600
	s_waitcnt vmcnt(5)
	ds_write_b32 v103, v42 offset:6864
	s_waitcnt vmcnt(4)
	ds_write_b32 v103, v43 offset:7128
	s_waitcnt vmcnt(3)
	ds_write_b32 v103, v44 offset:7392
	s_waitcnt vmcnt(2)
	ds_write_b32 v103, v45 offset:7656
	s_waitcnt vmcnt(1)
	ds_write_b32 v103, v46 offset:7920
	s_waitcnt vmcnt(0)
	ds_write_b32 v103, v47 offset:8184
	s_waitcnt lgkmcnt(0)
	ds_read_b32 v48, v106 offset:0
	ds_read_b32 v49, v106 offset:132
	ds_read_b32 v50, v106 offset:264
	ds_read_b32 v51, v106 offset:396
	ds_read_b32 v52, v106 offset:528
	ds_read_b32 v53, v106 offset:660
	ds_read_b32 v54, v106 offset:792
	ds_read_b32 v55, v106 offset:924
	s_waitcnt lgkmcnt(0)
	v_cvt_pk_bf16_f32 v80, v48, v49
	v_cvt_pk_bf16_f32 v81, v50, v51
	v_cvt_pk_bf16_f32 v82, v52, v53
	v_cvt_pk_bf16_f32 v83, v54, v55
	global_store_dwordx4 v108, v[80:83], s[14:15] nt
	s_add_u32 s14, s14, s19
	s_addc_u32 s15, s15, 0
	ds_read_b32 v56, v106 offset:32
	ds_read_b32 v57, v106 offset:164
	ds_read_b32 v58, v106 offset:296
	ds_read_b32 v59, v106 offset:428
	ds_read_b32 v60, v106 offset:560
	ds_read_b32 v61, v106 offset:692
	ds_read_b32 v62, v106 offset:824
	ds_read_b32 v63, v106 offset:956
	s_waitcnt lgkmcnt(0)
	v_cvt_pk_bf16_f32 v84, v56, v57
	v_cvt_pk_bf16_f32 v85, v58, v59
	v_cvt_pk_bf16_f32 v86, v60, v61
	v_cvt_pk_bf16_f32 v87, v62, v63
	global_store_dwordx4 v108, v[84:87], s[14:15] nt
	s_add_u32 s14, s14, s19
	s_addc_u32 s15, s15, 0
	ds_read_b32 v64, v106 offset:64
	ds_read_b32 v65, v106 offset:196
	ds_read_b32 v66, v106 offset:328
	ds_read_b32 v67, v106 offset:460
	ds_read_b32 v68, v106 offset:592
	ds_read_b32 v69, v106 offset:724
	ds_read_b32 v70, v106 offset:856
	ds_read_b32 v71, v106 offset:988
	s_waitcnt lgkmcnt(0)
	v_cvt_pk_bf16_f32 v88, v64, v65
	v_cvt_pk_bf16_f32 v89, v66, v67
	v_cvt_pk_bf16_f32 v90, v68, v69
	v_cvt_pk_bf16_f32 v91, v70, v71
	global_store_dwordx4 v108, v[88:91], s[14:15] nt
	s_add_u32 s14, s14, s19
	s_addc_u32 s15, s15, 0
	ds_read_b32 v72, v106 offset:96
	ds_read_b32 v73, v106 offset:228
	ds_read_b32 v74, v106 offset:360
	ds_read_b32 v75, v106 offset:492
	ds_read_b32 v76, v106 offset:624
	ds_read_b32 v77, v106 offset:756
	ds_read_b32 v78, v106 offset:888
	ds_read_b32 v79, v106 offset:1020
	s_waitcnt lgkmcnt(0)
	v_cvt_pk_bf16_f32 v92, v72, v73
	v_cvt_pk_bf16_f32 v93, v74, v75
	v_cvt_pk_bf16_f32 v94, v76, v77
	v_cvt_pk_bf16_f32 v95, v78, v79
	global_store_dwordx4 v108, v[92:95], s[14:15] nt
	s_add_i32 s6, s6, s7
	s_cmpk_lt_u32 s6, 4544
	s_cbranch_scc1 .Lcv0_item

.Lcv3_go:
	s_mul_i32 s1, s17, s12
	s_add_i32 s1, s1, s18
	s_lshl_b32 s1, s1, 2
	s_add_u32 s10, s10, s1
	s_addc_u32 s11, s11, 0
	v_mul_lo_u32 v8, v3, s12
	v_add_lshl_u32 v8, v8, v2, 2
	s_lshl_b32 s19, s12, 3
	global_load_dword v16, v8, s[10:11] nt
	s_add_u32 s10, s10, s19
	s_addc_u32 s11, s11, 0
	global_load_dword v17, v8, s[10:11] nt
	s_add_u32 s10, s10, s19
	s_addc_u32 s11, s11, 0
	global_load_dword v18, v8, s[10:11] nt
	s_add_u32 s10, s10, s19
	s_addc_u32 s11, s11, 0
	global_load_dword v19, v8, s[10:11] nt
	s_add_u32 s10, s10, s19
	s_addc_u32 s11, s11, 0
	global_load_dword v20, v8, s[10:11] nt
	s_add_u32 s10, s10, s19
	s_addc_u32 s11, s11, 0
	global_load_dword v21, v8, s[10:11] nt
	s_add_u32 s10, s10, s19
	s_addc_u32 s11, s11, 0
	global_load_dword v22, v8, s[10:11] nt
	s_add_u32 s10, s10, s19
	s_addc_u32 s11, s11, 0
	global_load_dword v23, v8, s[10:11] nt
	s_add_u32 s10, s10, s19
	s_addc_u32 s11, s11, 0
	global_load_dword v24, v8, s[10:11] nt
	s_add_u32 s10, s10, s19
	s_addc_u32 s11, s11, 0
	global_load_dword v25, v8, s[10:11] nt
	s_add_u32 s10, s10, s19
	s_addc_u32 s11, s11, 0
	global_load_dword v26, v8, s[10:11] nt
	s_add_u32 s10, s10, s19
	s_addc_u32 s11, s11, 0
	global_load_dword v27, v8, s[10:11] nt
	s_add_u32 s10, s10, s19
	s_addc_u32 s11, s11, 0
	global_load_dword v28, v8, s[10:11] nt
	s_add_u32 s10, s10, s19
	s_addc_u32 s11, s11, 0
	global_load_dword v29, v8, s[10:11] nt
	s_add_u32 s10, s10, s19
	s_addc_u32 s11, s11, 0
	global_load_dword v30, v8, s[10:11] nt
	s_add_u32 s10, s10, s19
	s_addc_u32 s11, s11, 0
	global_load_dword v31, v8, s[10:11] nt
	s_add_u32 s10, s10, s19
	s_addc_u32 s11, s11, 0
	global_load_dword v32, v8, s[10:11] nt
	s_add_u32 s10, s10, s19
	s_addc_u32 s11, s11, 0
	global_load_dword v33, v8, s[10:11] nt
	s_add_u32 s10, s10, s19
	s_addc_u32 s11, s11, 0
	global_load_dword v34, v8, s[10:11] nt
	s_add_u32 s10, s10, s19
	s_addc_u32 s11, s11, 0
	global_load_dword v35, v8, s[10:11] nt
	s_add_u32 s10, s10, s19
	s_addc_u32 s11, s11, 0
	global_load_dword v36, v8, s[10:11] nt
	s_add_u32 s10, s10, s19
	s_addc_u32 s11, s11, 0
	global_load_dword v37, v8, s[10:11] nt
	s_add_u32 s10, s10, s19
	s_addc_u32 s11, s11, 0
	global_load_dword v38, v8, s[10:11] nt
	s_add_u32 s10, s10, s19
	s_addc_u32 s11, s11, 0
	global_load_dword v39, v8, s[10:11] nt
	s_add_u32 s10, s10, s19
	s_addc_u32 s11, s11, 0
	global_load_dword v40, v8, s[10:11] nt
	s_add_u32 s10, s10, s19
	s_addc_u32 s11, s11, 0
	global_load_dword v41, v8, s[10:11] nt
	s_add_u32 s10, s10, s19
	s_addc_u32 s11, s11, 0
	global_load_dword v42, v8, s[10:11] nt
	s_add_u32 s10, s10, s19
	s_addc_u32 s11, s11, 0
	global_load_dword v43, v8, s[10:11] nt
	s_add_u32 s10, s10, s19
	s_addc_u32 s11, s11, 0
	global_load_dword v44, v8, s[10:11] nt
	s_add_u32 s10, s10, s19
	s_addc_u32 s11, s11, 0
	global_load_dword v45, v8, s[10:11] nt
	s_add_u32 s10, s10, s19
	s_addc_u32 s11, s11, 0
	global_load_dword v46, v8, s[10:11] nt
	s_add_u32 s10, s10, s19
	s_addc_u32 s11, s11, 0
	global_load_dword v47, v8, s[10:11] nt
	s_mul_i32 s1, s16, s13
	s_add_i32 s1, s1, s17
	s_lshl_b32 s1, s1, 1
	s_add_u32 s14, s14, s1
	s_addc_u32 s15, s15, 0
	v_mul_lo_u32 v9, v6, s13
	v_lshl_add_u32 v80, v5, 3, v9
	v_lshlrev_b32_e32 v9, 1, v80
	s_lshl_b32 s19, s13, 4
	s_waitcnt vmcnt(31)
	ds_write_b32 v4, v16 offset:0
	s_waitcnt vmcnt(30)
	ds_write_b32 v4, v17 offset:264
	s_waitcnt vmcnt(29)
	ds_write_b32 v4, v18 offset:528
	s_waitcnt vmcnt(28)
	ds_write_b32 v4, v19 offset:792
	s_waitcnt vmcnt(27)
	ds_write_b32 v4, v20 offset:1056
	s_waitcnt vmcnt(26)
	ds_write_b32 v4, v21 offset:1320
	s_waitcnt vmcnt(25)
	ds_write_b32 v4, v22 offset:1584
	s_waitcnt vmcnt(24)
	ds_write_b32 v4, v23 offset:1848
	s_waitcnt vmcnt(23)
	ds_write_b32 v4, v24 offset:2112
	s_waitcnt vmcnt(22)
	ds_write_b32 v4, v25 offset:2376
	s_waitcnt vmcnt(21)
	ds_write_b32 v4, v26 offset:2640
	s_waitcnt vmcnt(20)
	ds_write_b32 v4, v27 offset:2904
	s_waitcnt vmcnt(19)
	ds_write_b32 v4, v28 offset:3168
	s_waitcnt vmcnt(18)
	ds_write_b32 v4, v29 offset:3432
	s_waitcnt vmcnt(17)
	ds_write_b32 v4, v30 offset:3696
	s_waitcnt vmcnt(16)
	ds_write_b32 v4, v31 offset:3960
	s_waitcnt vmcnt(15)
	ds_write_b32 v4, v32 offset:4224
	s_waitcnt vmcnt(14)
	ds_write_b32 v4, v33 offset:4488
	s_waitcnt vmcnt(13)
	ds_write_b32 v4, v34 offset:4752
	s_waitcnt vmcnt(12)
	ds_write_b32 v4, v35 offset:5016
	s_waitcnt vmcnt(11)
	ds_write_b32 v4, v36 offset:5280
	s_waitcnt vmcnt(10)
	ds_write_b32 v4, v37 offset:5544
	s_waitcnt vmcnt(9)
	ds_write_b32 v4, v38 offset:5808
	s_waitcnt vmcnt(8)
	ds_write_b32 v4, v39 offset:6072
	s_waitcnt vmcnt(7)
	ds_write_b32 v4, v40 offset:6336
	s_waitcnt vmcnt(6)
	ds_write_b32 v4, v41 offset:6600
	s_waitcnt vmcnt(5)
	ds_write_b32 v4, v42 offset:6864
	s_waitcnt vmcnt(4)
	ds_write_b32 v4, v43 offset:7128
	s_waitcnt vmcnt(3)
	ds_write_b32 v4, v44 offset:7392
	s_waitcnt vmcnt(2)
	ds_write_b32 v4, v45 offset:7656
	s_waitcnt vmcnt(1)
	ds_write_b32 v4, v46 offset:7920
	s_waitcnt vmcnt(0)
	ds_write_b32 v4, v47 offset:8184
	s_waitcnt lgkmcnt(0)
	ds_read_b32 v48, v7 offset:0
	ds_read_b32 v49, v7 offset:132
	ds_read_b32 v50, v7 offset:264
	ds_read_b32 v51, v7 offset:396
	ds_read_b32 v52, v7 offset:528
	ds_read_b32 v53, v7 offset:660
	ds_read_b32 v54, v7 offset:792
	ds_read_b32 v55, v7 offset:924
	s_waitcnt lgkmcnt(0)
	v_cvt_pk_bf16_f32 v80, v48, v49
	v_cvt_pk_bf16_f32 v81, v50, v51
	v_cvt_pk_bf16_f32 v82, v52, v53
	v_cvt_pk_bf16_f32 v83, v54, v55
	global_store_dwordx4 v9, v[80:83], s[14:15] nt
	s_add_u32 s14, s14, s19
	s_addc_u32 s15, s15, 0
	ds_read_b32 v56, v7 offset:32
	ds_read_b32 v57, v7 offset:164
	ds_read_b32 v58, v7 offset:296
	ds_read_b32 v59, v7 offset:428
	ds_read_b32 v60, v7 offset:560
	ds_read_b32 v61, v7 offset:692
	ds_read_b32 v62, v7 offset:824
	ds_read_b32 v63, v7 offset:956
	s_waitcnt lgkmcnt(0)
	v_cvt_pk_bf16_f32 v84, v56, v57
	v_cvt_pk_bf16_f32 v85, v58, v59
	v_cvt_pk_bf16_f32 v86, v60, v61
	v_cvt_pk_bf16_f32 v87, v62, v63
	global_store_dwordx4 v9, v[84:87], s[14:15] nt
	s_add_u32 s14, s14, s19
	s_addc_u32 s15, s15, 0
	ds_read_b32 v64, v7 offset:64
	ds_read_b32 v65, v7 offset:196
	ds_read_b32 v66, v7 offset:328
	ds_read_b32 v67, v7 offset:460
	ds_read_b32 v68, v7 offset:592
	ds_read_b32 v69, v7 offset:724
	ds_read_b32 v70, v7 offset:856
	ds_read_b32 v71, v7 offset:988
	s_waitcnt lgkmcnt(0)
	v_cvt_pk_bf16_f32 v88, v64, v65
	v_cvt_pk_bf16_f32 v89, v66, v67
	v_cvt_pk_bf16_f32 v90, v68, v69
	v_cvt_pk_bf16_f32 v91, v70, v71
	global_store_dwordx4 v9, v[88:91], s[14:15] nt
	s_add_u32 s14, s14, s19
	s_addc_u32 s15, s15, 0
	ds_read_b32 v72, v7 offset:96
	ds_read_b32 v73, v7 offset:228
	ds_read_b32 v74, v7 offset:360
	ds_read_b32 v75, v7 offset:492
	ds_read_b32 v76, v7 offset:624
	ds_read_b32 v77, v7 offset:756
	ds_read_b32 v78, v7 offset:888
	ds_read_b32 v79, v7 offset:1020
	s_waitcnt lgkmcnt(0)
	v_cvt_pk_bf16_f32 v92, v72, v73
	v_cvt_pk_bf16_f32 v93, v74, v75
	v_cvt_pk_bf16_f32 v94, v76, v77
	v_cvt_pk_bf16_f32 v95, v78, v79
	global_store_dwordx4 v9, v[92:95], s[14:15] nt
	s_add_i32 s6, s6, s7
	s_cmpk_lt_u32 s6, 4736
	s_cbranch_scc1 .Lcv3_item
